# top-k rewrite applied to the executed (paired-grid) compressed-attention path as well
# speedup vs baseline: 1.0053x; 1.0053x over previous
; __device__ __forceinline__ int dpp_x1(int x) { return __builtin_amdgcn_update_dpp(0, x, 0xB1, 0xF, 0xF, true); }
; __device__ __forceinline__ int dpp_x2(int x) { return __builtin_amdgcn_update_dpp(0, x, 0x4E, 0xF, 0xF, true); }
; __device__ __forceinline__ int quad_isum(int v) { v += dpp_x1(v); v += dpp_x2(v); return v; }
; __device__ __forceinline__ int half_isum(int v) { auto rr = __builtin_amdgcn_permlane32_swap((unsigned)v, (unsigned)v, false, false); return (int)(rr[0] + rr[1]); }
; __device__ __forceinline__ void cmp_task_lds(const Prm& P, Ctx& C, int b, int kvh, int tg, CStream& CS, const LAS bf16_t* wlb, const int NGW, bf16x8 (&qnx)[4], int& qnx_tg, const int tg_next) {
;     ...
;             for (int it = 0; it < 15; ++it) {
;                 unsigned t[16];
; #pragma unroll
;                 for (int e = 0; e < 16; ++e) t[e] = v[e] < ceil_ ? v[e] : 0u;
; #pragma unroll
;                 for (int st = 8; st >= 1; st >>= 1)
; #pragma unroll
;                     for (int e = 0; e < st; ++e) t[e] = t[e] > t[e + st] ? t[e] : t[e + st];
;                 unsigned mx = t[0];
;                 { const unsigned o1 = (unsigned)dpp_x1((int)mx); mx = mx > o1 ? mx : o1; const unsigned o2 = (unsigned)dpp_x2((int)mx); mx = mx > o2 ? mx : o2;
;                   auto rr = __builtin_amdgcn_permlane32_swap(mx, mx, false, false); mx = rr[0] > rr[1] ? rr[0] : rr[1]; }
;                 int c4[4] = {0, 0, 0, 0};
; #pragma unroll
;                 for (int e = 0; e < 16; ++e) c4[e & 3] += (v[e] == mx) ? 1 : 0;
;                 const int c = half_isum(quad_isum((c4[0] + c4[1]) + (c4[2] + c4[3])));
;                 if (!done) { taken += c; if (taken >= kk) { prefix = mx; done = true; } else ceil_ = mx; }
.LBB0_1309:
	s_xor_b64 s[56:57], s[54:55], -1
	s_or_b64 s[52:53], s[52:53], exec
	v_add_u32_e32 v45, -1, v21
	v_sub_u32_e32 v37, v45, v28
	v_sub_u32_e32 v38, v45, v26
	v_sub_u32_e32 v39, v45, v25
	v_sub_u32_e32 v40, v45, v7
	v_sub_u32_e32 v41, v45, v8
	v_sub_u32_e32 v42, v45, v5
	v_min3_u32 v37, v37, v38, v39
	v_sub_u32_e32 v38, v45, v6
	v_sub_u32_e32 v39, v45, v22
	v_sub_u32_e32 v43, v45, v27
	v_min3_u32 v40, v40, v41, v42
	v_sub_u32_e32 v41, v45, v35
	v_sub_u32_e32 v42, v45, v34
	v_sub_u32_e32 v44, v45, v33
	v_min3_u32 v38, v38, v39, v43
	v_sub_u32_e32 v39, v45, v32
	v_sub_u32_e32 v43, v45, v31
	v_min3_u32 v41, v41, v42, v44
	v_sub_u32_e32 v42, v45, v30
	v_sub_u32_e32 v44, v45, v29
	v_min3_u32 v39, v39, v43, v42
	v_min3_u32 v37, v37, v40, v38
	v_min3_u32 v39, v41, v39, v44
	v_min_u32_e32 v37, v37, v39
	s_nop 1
	v_min_u32_dpp v37, v37, v37 quad_perm:[1,0,3,2] row_mask:0xf bank_mask:0xf bound_ctrl:1
	s_nop 1
	v_min_u32_dpp v37, v37, v37 quad_perm:[2,3,0,1] row_mask:0xf bank_mask:0xf bound_ctrl:1
	v_mov_b32_e32 v38, v37
	s_nop 1
	v_permlane32_swap_b32_e32 v37, v38
	v_min_u32_e32 v37, v37, v38
	v_sub_u32_e32 v37, v45, v37
	v_xor_b32_e32 v38, v28, v37
	v_xor_b32_e32 v39, v26, v37
	v_xor_b32_e32 v40, v25, v37
	v_min_u32_e32 v38, 1, v38
	v_min_u32_e32 v39, 1, v39
	v_min_u32_e32 v40, 1, v40
	v_add3_u32 v38, v38, v39, v40
	v_xor_b32_e32 v39, v7, v37
	v_xor_b32_e32 v40, v8, v37
	v_min_u32_e32 v39, 1, v39
	v_min_u32_e32 v40, 1, v40
	v_add3_u32 v38, v38, v39, v40
	v_xor_b32_e32 v41, v5, v37
	v_xor_b32_e32 v42, v6, v37
	v_min_u32_e32 v41, 1, v41
	v_min_u32_e32 v42, 1, v42
	v_add3_u32 v38, v38, v41, v42
	v_xor_b32_e32 v39, v22, v37
	v_xor_b32_e32 v40, v27, v37
	v_min_u32_e32 v39, 1, v39
	v_min_u32_e32 v40, 1, v40
	v_add3_u32 v38, v38, v39, v40
	v_xor_b32_e32 v41, v35, v37
	v_xor_b32_e32 v42, v34, v37
	v_min_u32_e32 v41, 1, v41
	v_min_u32_e32 v42, 1, v42
	v_add3_u32 v38, v38, v41, v42
	v_xor_b32_e32 v39, v33, v37
	v_xor_b32_e32 v40, v32, v37
	v_min_u32_e32 v39, 1, v39
	v_min_u32_e32 v40, 1, v40
	v_add3_u32 v38, v38, v39, v40
	v_xor_b32_e32 v41, v31, v37
	v_xor_b32_e32 v42, v30, v37
	v_min_u32_e32 v41, 1, v41
	v_min_u32_e32 v42, 1, v42
	v_add3_u32 v38, v38, v41, v42
	v_xor_b32_e32 v39, v29, v37
	v_min_u32_e32 v39, 1, v39
	v_add_u32_e32 v38, v38, v39
	v_sub_u32_e32 v38, 16, v38
	s_nop 1
	v_add_u32_dpp v38, v38, v38 quad_perm:[1,0,3,2] row_mask:0xf bank_mask:0xf bound_ctrl:1
	s_nop 1
	v_add_u32_dpp v38, v38, v38 quad_perm:[2,3,0,1] row_mask:0xf bank_mask:0xf bound_ctrl:1
	v_mov_b32_e32 v39, v38
	s_nop 1
	v_permlane32_swap_b32_e32 v38, v39
	s_and_saveexec_b64 s[58:59], s[56:57]
	s_cbranch_execz .LBB0_1308
	v_add3_u32 v24, v39, v24, v38
	v_cmp_le_i32_e32 vcc, s78, v24
	s_andn2_b64 s[52:53], s[52:53], exec
	s_and_b64 s[54:55], vcc, exec
	v_cndmask_b32_e32 v23, v23, v37, vcc
	v_cndmask_b32_e32 v21, v37, v21, vcc
	s_or_b64 s[52:53], s[52:53], s[54:55]
	s_branch .LBB0_1308
